# v81 + phase-2 jobs (p->bf16, w_ple^T) only on the 1-item z-path workgroups (bid>=128), stride 128
# speedup vs baseline: 1.0109x; 1.0109x over previous
.LBB0_275:
	s_or_b64 exec, exec, s[0:1]
	s_cmpk_lg_u32 s3, 0x100
	s_cbranch_scc1 .Lp2_jobs_keep
	s_cmpk_ge_i32 s25, 0x40
	s_cbranch_scc1 .Lp2_jobs_hi
	s_movk_i32 s25, 0x7000
	s_branch .Lp2_jobs_keep
.Lp2_jobs_hi:
	s_addk_i32 s25, 0xffc0
	s_movk_i32 s24, 0x80
.Lp2_jobs_keep:
	v_readlane_b32 s36, v254, 40
	s_cmpk_gt_i32 s25, 0x20f
	v_readlane_b32 s37, v254, 41
	s_cbranch_scc1 .LBB0_364
	s_add_u32 s10, s78, 0x3200000
	s_addc_u32 s11, s79, 0
	s_add_u32 s0, s78, 0x600000
	v_readlane_b32 s36, v254, 5
	s_addc_u32 s1, s79, 0
	v_readlane_b32 s37, v254, 6
	v_readlane_b32 s38, v254, 7
	v_readlane_b32 s39, v254, 8
	v_readlane_b32 s40, v254, 9
	v_readlane_b32 s41, v254, 10
	v_readlane_b32 s42, v254, 11
	v_readlane_b32 s43, v254, 12
	v_readlane_b32 s44, v254, 13
	v_readlane_b32 s45, v254, 14
	v_readlane_b32 s46, v254, 15
	v_readlane_b32 s47, v254, 16
	v_readlane_b32 s48, v254, 17
	v_readlane_b32 s49, v254, 18
	v_readlane_b32 s50, v254, 19
	v_readlane_b32 s51, v254, 20
	v_writelane_b32 v254, s0, 42
	v_lshlrev_b32_e32 v70, 3, v1
	v_and_b32_e32 v4, 0xf8, v70
	v_writelane_b32 v254, s1, 43
	s_add_u32 s0, s78, 0x580000
	s_addc_u32 s1, s79, 0
	v_writelane_b32 v254, s0, 44
	v_mul_u32_u24_e32 v6, 0x41, v4
	v_lshrrev_b32_e32 v97, 5, v1
	v_writelane_b32 v254, s1, 45
	s_add_u32 s0, s78, 0x380000
	v_lshlrev_b32_e32 v6, 2, v6
	s_addc_u32 s1, s79, 0
	v_lshlrev_b32_e32 v7, 2, v97
	v_add_u32_e32 v8, 0, v6
	v_writelane_b32 v254, s0, 46
	v_add3_u32 v99, 0, v7, v6
	v_add_u32_e32 v100, v8, v7
	v_add_u32_e32 v7, 0x200, v1
	v_lshrrev_b32_e32 v2, 4, v1
	v_mov_b32_e32 v3, 0xffff9800
	v_writelane_b32 v254, s1, 47
	s_add_u32 s0, s78, 0x180000
	v_lshrrev_b32_e32 v101, 5, v7
	v_and_or_b32 v71, v2, 60, v3
	v_lshlrev_b32_e32 v3, 2, v1
	s_addc_u32 s1, s79, 0
	s_movk_i32 s2, 0xf8
	v_lshlrev_b32_e32 v7, 2, v101
	v_and_b32_e32 v5, 0xfc, v3
	v_writelane_b32 v254, s0, 48
	v_add3_u32 v102, 0, v7, v6
	v_add_u32_e32 v103, v8, v7
	v_add_u32_e32 v7, 0x600, v1
	v_bitop3_b32 v3, v3, s2, v3 bitop3:0xc
	v_writelane_b32 v254, s1, 49
	s_add_u32 s0, s78, 0x80000
	v_lshrrev_b32_e32 v105, 5, v7
	v_add_u32_e32 v111, 0, v3
	v_lshlrev_b32_e32 v3, 6, v1
	s_addc_u32 s1, s79, 0
	v_lshlrev_b32_e32 v7, 2, v105
	v_and_b32_e32 v3, 64, v3
	v_mov_b32_e32 v73, 0
	v_lshlrev_b32_e32 v72, 2, v5
	s_add_u32 s34, s78, 0x800000
	v_add_u32_e32 v107, v8, v7
	v_mul_u32_u24_e32 v8, 0x78, v1
	v_add_u32_e32 v112, 0, v3
	v_lshlrev_b32_e32 v3, 4, v1
	v_lshl_add_u64 v[74:75], s[36:37], 0, v[72:73]
	v_lshl_add_u64 v[76:77], s[40:41], 0, v[72:73]
	s_addc_u32 s35, s79, 0
	v_mul_u32_u24_e32 v10, 0x88, v1
	v_bfe_u32 v109, v1, 4, 2
	v_and_b32_e32 v72, 0x3f0, v3
	v_add3_u32 v3, v8, v70, 0
	s_movk_i32 s2, 0x4200
	v_and_b32_e32 v2, 63, v1
	s_add_u32 s52, s78, 0x1600000
	v_and_b32_e32 v110, 15, v1
	v_add_u32_e32 v113, 0x200, v3
	v_add3_u32 v114, v3, v10, s2
	v_lshl_add_u32 v3, v109, 9, 0
	v_lshrrev_b32_e32 v93, 6, v1
	v_lshl_add_u32 v95, v2, 2, 0
	s_addc_u32 s53, s79, 0
	v_add_u32_e32 v108, 0, v70
	s_movk_i32 s4, 0x78
	v_add_u32_e32 v117, 0x2200, v3
	v_lshl_add_u32 v3, v110, 3, 0
	v_lshlrev_b32_e32 v82, 2, v2
	v_writelane_b32 v254, s0, 50
	v_add3_u32 v106, 0, v7, v6
	s_add_u32 s54, s78, 0xe800000
	v_mad_u32_u24 v9, v1, s4, v108
	v_lshl_add_u64 v[6:7], s[78:79], 0, v[72:73]
	s_mov_b64 s[4:5], 0x2a00000
	v_lshlrev_b32_e32 v72, 1, v5
	v_add_u32_e32 v118, 0x200, v3
	v_lshl_add_u32 v3, v93, 3, 0
	v_mbcnt_lo_u32_b32 v2, -1, 0
	v_writelane_b32 v254, s1, 51
	s_mov_b32 s51, 0
	v_or_b32_e32 v104, 32, v97
	s_addc_u32 s55, s79, 0
	v_cmp_gt_u32_e64 s[0:1], 64, v1
	v_lshl_add_u64 v[78:79], v[6:7], 0, s[4:5]
	v_lshl_add_u64 v[80:81], s[76:77], 0, v[72:73]
	v_add_u32_e32 v115, 0x2200, v108
	v_add_u32_e32 v116, 0xfffffe00, v1
	v_add_u32_e32 v119, 0x4200, v3
	s_mov_b32 s56, 0x3a800000
	s_mov_b32 s57, 0x800000
	v_lshlrev_b32_e32 v84, 1, v4
	s_mov_b32 s2, s96
	s_mov_b32 s96, 0x3fb8aa3b
	s_mov_b32 s97, 0xc2ce8ed0
	s_mov_b32 s14, 0x42b17218
	s_mov_b32 s15, 0xfe5163ab
	s_mov_b32 s12, 0x3c439041
	s_mov_b32 s13, 0xdb629599
	s_mov_b32 s16, 0xf534ddc0
	s_mov_b32 s17, 0xfc2757d1
	s_mov_b32 s20, 0x4e441529
	s_mov_b32 s21, 0xa2f9836e
	s_mov_b32 s22, 0x3fc90fda
	s_mov_b32 s23, 0xbfc90fda
	v_mov_b32_e32 v120, 0x3c0881c4
	v_mov_b32_e32 v121, 0xbab64f3b
	v_add_u32_e32 v122, v9, v10
	s_mov_b64 s[58:59], 0x800
	v_mbcnt_hi_u32_b32 v123, -1, v2
	v_mov_b32_e32 v124, 0x7f800000
	v_not_b32_e32 v125, 63
	v_not_b32_e32 v126, 31
	v_mov_b32_e32 v127, 0x7fc00000
	s_branch .LBB0_278
